# anorm row pass: next row's cache lines touched one trip ahead (two dummy dword loads per lane), counted waits adjusted
# baseline (speedup 1.0000x reference)
; DEVI unsigned pk_bf16(float lo, float hi) { unsigned r; asm("v_cvt_pk_bf16_f32 %0, %1, %2" : "=v"(r) : "v"(lo), "v"(hi)); return r; }
; DEVI float bf_lo(unsigned u) { return __uint_as_float(u << 16); }
; DEVI float bf_hi(unsigned u) { return __uint_as_float(u & 0xffff0000u); }
; DEVI float sigmoidf_(float x) { return __builtin_amdgcn_rcpf(1.0f + __builtin_amdgcn_exp2f(-x * LOG2E)); }
; __device__ __forceinline__ void anorm_phase(const Params& p) {
;     ...
;   for (int r = wave; r < M; r += nw) {
;     bf16_t* zr = Z + (size_t)r * LDZE;
;     const uint4 h0 = *(const uint4*)(zr + 1024 + 16 * lane), h1 = *(const uint4*)(zr + 1024 + 16 * lane + 8);
;     const uint4 o0 = *(const uint4*)(zr + 3072 + 16 * lane), o1 = *(const uint4*)(zr + 3072 + 16 * lane + 8);
;     const unsigned hu[8] = {h0.x, h0.y, h0.z, h0.w, h1.x, h1.y, h1.z, h1.w}, ou[8] = {o0.x, o0.y, o0.z, o0.w, o1.x, o1.y, o1.z, o1.w};
;     float hv[16], ov[16]; float ss = 0.f;
; #pragma unroll
;     for (int i = 0; i < 8; ++i) { hv[2 * i] = bf_lo(hu[i]); hv[2 * i + 1] = bf_hi(hu[i]); ov[2 * i] = bf_lo(ou[i]); ov[2 * i + 1] = bf_hi(ou[i]); ss += hv[2 * i] * hv[2 * i] + hv[2 * i + 1] * hv[2 * i + 1]; }
;     ss += __shfl_xor(ss, 1); ss += __shfl_xor(ss, 2); ss += __shfl_xor(ss, 4); ss += __shfl_xor(ss, 8);
;     const float rs = rsqrtf(ss * (1.0f / 256.0f) + EPS);
;     const float* gp = p.ev_a_norm + ((16 * lane) & 255);
;     unsigned res[8];
; #pragma unroll
;     for (int i = 0; i < 8; ++i) res[i] = pk_bf16(hv[2 * i] * rs * gp[2 * i] * sigmoidf_(ov[2 * i]), hv[2 * i + 1] * rs * gp[2 * i + 1] * sigmoidf_(ov[2 * i + 1]));
;     *(uint4*)(zr + 3072 + 16 * lane) = make_uint4(res[0], res[1], res[2], res[3]);
;     *(uint4*)(zr + 3072 + 16 * lane + 8) = make_uint4(res[4], res[5], res[6], res[7]);
;   }
.LBB0_790:
	global_load_dwordx4 v[24:27], v[14:15], off
	global_load_dwordx4 v[8:11], v[14:15], off offset:16
	v_add_co_u32_e32 v16, vcc, 0x1000, v14
	v_lshl_add_u64 v[40:41], v[14:15], 0, s[6:7]
	s_nop 0
	v_addc_co_u32_e32 v17, vcc, 0, v15, vcc
	global_load_dwordx4 v[0:3], v[12:13], off
	global_load_dwordx4 v[4:7], v[12:13], off offset:16
	global_load_dwordx4 v[28:31], v[12:13], off offset:32
	global_load_dwordx4 v[32:35], v[12:13], off offset:48
	global_load_dwordx4 v[36:39], v[16:17], off
	s_nop 0
	global_load_dwordx4 v[40:43], v[40:41], off offset:16
	v_add_u32_e32 v18, s20, v18
	v_cmp_lt_i32_e32 vcc, s9, v18
	s_or_b64 s[4:5], vcc, s[4:5]
	v_lshl_add_u64 v[14:15], v[14:15], 0, s[2:3]
	v_cndmask_b32_e64 v122, v14, v16, s[4:5]
	v_cndmask_b32_e64 v123, v15, v17, s[4:5]
	global_load_dword v120, v[122:123], off
	v_lshl_add_u64 v[122:123], v[122:123], 0, s[6:7]
	global_load_dword v121, v[122:123], off
	s_waitcnt vmcnt(9)
	v_lshlrev_b32_e32 v54, 16, v24
	v_lshlrev_b32_e32 v56, 16, v25
	v_and_b32_e32 v55, 0xffff0000, v24
	v_and_b32_e32 v57, 0xffff0000, v25
	v_lshlrev_b32_e32 v25, 16, v27
	v_lshlrev_b32_e32 v24, 16, v26
	s_waitcnt vmcnt(8)
	v_lshlrev_b32_e32 v47, 16, v11
	v_lshlrev_b32_e32 v46, 16, v10
	v_mul_f32_e32 v58, v54, v54
	v_mul_f32_e32 v59, v56, v56
	v_and_b32_e32 v27, 0xffff0000, v27
	v_and_b32_e32 v26, 0xffff0000, v26
	v_and_b32_e32 v11, 0xffff0000, v11
	v_and_b32_e32 v10, 0xffff0000, v10
	v_pk_mul_f32 v[48:49], v[24:25], v[24:25]
	v_pk_mul_f32 v[52:53], v[46:47], v[46:47]
	v_fmac_f32_e32 v58, v55, v55
	v_fmac_f32_e32 v59, v57, v57
	v_lshlrev_b32_e32 v45, 16, v9
	v_lshlrev_b32_e32 v44, 16, v8
	s_waitcnt vmcnt(3)
	v_lshlrev_b32_e32 v60, 16, v36
	v_and_b32_e32 v61, 0xffff0000, v36
	v_lshlrev_b32_e32 v62, 16, v37
	v_and_b32_e32 v63, 0xffff0000, v37
	v_lshlrev_b32_e32 v64, 16, v38
	v_and_b32_e32 v65, 0xffff0000, v38
	v_lshlrev_b32_e32 v66, 16, v39
	v_and_b32_e32 v67, 0xffff0000, v39
	v_pk_fma_f32 v[36:37], v[26:27], v[26:27], v[48:49]
	s_waitcnt vmcnt(2)
	v_lshlrev_b32_e32 v48, 16, v40
	v_and_b32_e32 v49, 0xffff0000, v40
	v_lshlrev_b32_e32 v68, 16, v41
	v_and_b32_e32 v69, 0xffff0000, v41
	v_pk_fma_f32 v[40:41], v[10:11], v[10:11], v[52:53]
	v_add_f32_e32 v52, v58, v59
	v_and_b32_e32 v9, 0xffff0000, v9
	v_and_b32_e32 v8, 0xffff0000, v8
	v_pk_mul_f32 v[50:51], v[44:45], v[44:45]
	v_mul_f32_e32 v53, 0xbfb8aa3b, v60
	v_mul_f32_e32 v58, 0xbfb8aa3b, v61
	v_mul_f32_e32 v59, 0xbfb8aa3b, v62
	v_mul_f32_e32 v60, 0xbfb8aa3b, v63
	v_mul_f32_e32 v61, 0xbfb8aa3b, v64
	v_mul_f32_e32 v62, 0xbfb8aa3b, v65
	v_mul_f32_e32 v63, 0xbfb8aa3b, v66
	v_mul_f32_e32 v64, 0xbfb8aa3b, v67
	v_mul_f32_e32 v65, 0xbfb8aa3b, v68
	v_mul_f32_e32 v66, 0xbfb8aa3b, v69
	v_add_f32_e32 v36, v52, v36
	v_pk_fma_f32 v[38:39], v[8:9], v[8:9], v[50:51]
	v_exp_f32_e32 v52, v53
	v_exp_f32_e32 v53, v58
	v_exp_f32_e32 v58, v59
	v_exp_f32_e32 v59, v60
	v_exp_f32_e32 v60, v61
	v_exp_f32_e32 v61, v62
	v_exp_f32_e32 v62, v63
	v_exp_f32_e32 v63, v64
	v_exp_f32_e32 v64, v65
	v_exp_f32_e32 v65, v66
	v_add_f32_e32 v36, v36, v37
	v_add_f32_e32 v36, v36, v38
	v_add_f32_e32 v36, v36, v39
	v_add_f32_e32 v36, v36, v40
	v_add_f32_e32 v37, 1.0, v52
	v_add_f32_e32 v38, 1.0, v53
	v_add_f32_e32 v39, 1.0, v58
	v_add_f32_e32 v40, 1.0, v59
	v_add_f32_e32 v52, 1.0, v60
	v_add_f32_e32 v53, 1.0, v61
	v_add_f32_e32 v58, 1.0, v62
	v_add_f32_e32 v59, 1.0, v63
	v_add_f32_e32 v60, 1.0, v64
	v_add_f32_e32 v61, 1.0, v65
	v_add_f32_e32 v36, v36, v41
	v_rcp_f32_e32 v41, v52
	v_rcp_f32_e32 v52, v53
	v_rcp_f32_e32 v53, v58
	v_rcp_f32_e32 v58, v59
	v_rcp_f32_e32 v59, v60
	v_rcp_f32_e32 v60, v61
	ds_bpermute_b32 v61, v19, v36
	v_lshlrev_b32_e32 v50, 16, v42
	v_and_b32_e32 v42, 0xffff0000, v42
	v_lshlrev_b32_e32 v51, 16, v43
	v_and_b32_e32 v43, 0xffff0000, v43
	s_waitcnt lgkmcnt(0)
	v_add_f32_e32 v36, v36, v61
	ds_bpermute_b32 v61, v20, v36
	v_mul_f32_e32 v48, 0xbfb8aa3b, v48
	v_mul_f32_e32 v49, 0xbfb8aa3b, v49
	v_mul_f32_e32 v50, 0xbfb8aa3b, v50
	v_mul_f32_e32 v42, 0xbfb8aa3b, v42
	s_waitcnt lgkmcnt(0)
	v_add_f32_e32 v36, v36, v61
	ds_bpermute_b32 v61, v21, v36
	v_mul_f32_e32 v51, 0xbfb8aa3b, v51
	v_mul_f32_e32 v43, 0xbfb8aa3b, v43
	v_exp_f32_e32 v48, v48
	v_exp_f32_e32 v49, v49
	s_waitcnt lgkmcnt(0)
	v_add_f32_e32 v36, v36, v61
	ds_bpermute_b32 v61, v22, v36
	v_exp_f32_e32 v50, v50
	v_exp_f32_e32 v42, v42
	v_exp_f32_e32 v51, v51
	v_exp_f32_e32 v43, v43
	s_waitcnt lgkmcnt(0)
	v_add_f32_e32 v36, v36, v61
	v_fmamk_f32 v36, v36, 0x3b800000, v23
	v_mul_f32_e32 v61, 0x4b800000, v36
	v_cmp_gt_f32_e32 vcc, s8, v36
	v_rcp_f32_e32 v37, v37
	v_rcp_f32_e32 v38, v38
	v_cndmask_b32_e32 v36, v36, v61, vcc
	v_rsq_f32_e32 v36, v36
	v_rcp_f32_e32 v39, v39
	v_rcp_f32_e32 v40, v40
	v_add_f32_e32 v48, 1.0, v48
	v_mul_f32_e32 v61, 0x45800000, v36
	v_add_f32_e32 v49, 1.0, v49
	v_add_f32_e32 v50, 1.0, v50
	v_add_f32_e32 v42, 1.0, v42
	v_add_f32_e32 v51, 1.0, v51
	v_add_f32_e32 v43, 1.0, v43
	v_cndmask_b32_e32 v36, v36, v61, vcc
	v_rcp_f32_e32 v48, v48
	v_rcp_f32_e32 v49, v49
	v_rcp_f32_e32 v50, v50
	v_rcp_f32_e32 v42, v42
	v_rcp_f32_e32 v51, v51
	v_rcp_f32_e32 v43, v43
	v_mul_f32_e32 v54, v36, v54
	v_mul_f32_e32 v55, v36, v55
	v_mul_f32_e32 v56, v36, v56
	v_mul_f32_e32 v57, v36, v57
	v_mul_f32_e32 v24, v36, v24
	v_mul_f32_e32 v26, v36, v26
	v_mul_f32_e32 v25, v36, v25
	v_mul_f32_e32 v27, v36, v27
	v_mul_f32_e32 v0, v0, v54
	v_mul_f32_e32 v1, v1, v55
	v_mul_f32_e32 v2, v2, v56
	v_mul_f32_e32 v3, v3, v57
	v_mul_f32_e32 v44, v36, v44
	v_mul_f32_e32 v8, v36, v8
	v_mul_f32_e32 v45, v36, v45
	v_mul_f32_e32 v9, v36, v9
	v_mul_f32_e32 v46, v36, v46
	v_mul_f32_e32 v10, v36, v10
	v_mul_f32_e32 v47, v36, v47
	v_mul_f32_e32 v11, v36, v11
	v_mul_f32_e32 v4, v4, v24
	v_mul_f32_e32 v5, v5, v26
	v_mul_f32_e32 v6, v25, v6
	v_mul_f32_e32 v7, v27, v7
	v_mul_f32_e32 v0, v37, v0
	v_mul_f32_e32 v1, v38, v1
	v_mul_f32_e32 v2, v39, v2
	v_mul_f32_e32 v3, v40, v3
	v_mul_f32_e32 v24, v44, v28
	v_mul_f32_e32 v8, v8, v29
	v_mul_f32_e32 v25, v45, v30
	v_mul_f32_e32 v9, v9, v31
	v_mul_f32_e32 v26, v46, v32
	v_mul_f32_e32 v10, v10, v33
	v_mul_f32_e32 v27, v47, v34
	v_mul_f32_e32 v11, v11, v35
	v_mul_f32_e32 v4, v41, v4
	v_mul_f32_e32 v5, v52, v5
	v_mul_f32_e32 v6, v53, v6
	v_mul_f32_e32 v7, v58, v7
	v_cvt_pk_bf16_f32 v0, v0, v1
	v_cvt_pk_bf16_f32 v1, v2, v3
	v_cvt_pk_bf16_f32 v2, v4, v5
	v_cvt_pk_bf16_f32 v3, v6, v7
	v_mul_f32_e32 v24, v48, v24
	v_mul_f32_e32 v8, v49, v8
	v_mul_f32_e32 v25, v59, v25
	v_mul_f32_e32 v9, v60, v9
	v_mul_f32_e32 v26, v50, v26
	v_mul_f32_e32 v10, v42, v10
	v_mul_f32_e32 v27, v51, v27
	v_mul_f32_e32 v11, v43, v11
	v_cvt_pk_bf16_f32 v4, v24, v8
	v_cvt_pk_bf16_f32 v5, v25, v9
	v_cvt_pk_bf16_f32 v6, v26, v10
	v_cvt_pk_bf16_f32 v7, v27, v11
	global_store_dwordx4 v[16:17], v[0:3], off
	global_store_dwordx4 v[16:17], v[4:7], off offset:16
	s_andn2_b64 exec, exec, s[4:5]
	s_cbranch_execnz .LBB0_790
